# v90 + DSA selection after the threshold search rewritten compactly (32 ballots + LDS mask row, ties in slot/lane order), 1436 lines -> 686
# baseline (speedup 1.0000x reference)
.LBB0_776:
	v_readlane_b32 s34, v254, 58
	v_readlane_b32 s35, v254, 59
	v_readlane_b32 s36, v254, 63
	v_readlane_b32 s37, v255, 0
	s_mov_b64 s[10:11], exec
	v_mov_b32_e32 v1, s33
	s_mov_b32 s65, 0
	v_cmp_gt_u32_e64 s[70:71], v32, v0
	v_cmp_gt_u32_e64 s[72:73], v33, v0
	v_cmp_gt_u32_e64 s[74:75], v34, v0
	v_cmp_gt_u32_e64 s[76:77], v35, v0
	v_cmp_gt_u32_e64 s[78:79], v36, v0
	v_cmp_gt_u32_e64 s[80:81], v37, v0
	v_cmp_gt_u32_e64 s[82:83], v38, v0
	v_cmp_gt_u32_e64 s[84:85], v39, v0
	v_mov_b64_e32 v[2:3], s[70:71]
	v_mov_b64_e32 v[4:5], s[72:73]
	v_mov_b64_e32 v[6:7], s[74:75]
	v_mov_b64_e32 v[8:9], s[76:77]
	s_mov_b64 exec, s[20:21]
	ds_write_b128 v1, v[2:5] offset:0
	ds_write_b128 v1, v[6:9] offset:16
	s_mov_b64 exec, s[10:11]
	s_bcnt1_i32_b64 s6, s[70:71]
	s_add_i32 s65, s65, s6
	s_bcnt1_i32_b64 s6, s[72:73]
	s_add_i32 s65, s65, s6
	s_bcnt1_i32_b64 s6, s[74:75]
	s_add_i32 s65, s65, s6
	s_bcnt1_i32_b64 s6, s[76:77]
	s_add_i32 s65, s65, s6
	v_cmp_gt_u32_e64 s[70:71], v40, v0
	v_cmp_gt_u32_e64 s[72:73], v41, v0
	v_cmp_gt_u32_e64 s[74:75], v42, v0
	v_cmp_gt_u32_e64 s[76:77], v43, v0
	v_mov_b64_e32 v[2:3], s[78:79]
	v_mov_b64_e32 v[4:5], s[80:81]
	v_mov_b64_e32 v[6:7], s[82:83]
	v_mov_b64_e32 v[8:9], s[84:85]
	s_mov_b64 exec, s[20:21]
	ds_write_b128 v1, v[2:5] offset:32
	ds_write_b128 v1, v[6:9] offset:48
	s_mov_b64 exec, s[10:11]
	s_bcnt1_i32_b64 s6, s[78:79]
	s_add_i32 s65, s65, s6
	s_bcnt1_i32_b64 s6, s[80:81]
	s_add_i32 s65, s65, s6
	s_bcnt1_i32_b64 s6, s[82:83]
	s_add_i32 s65, s65, s6
	s_bcnt1_i32_b64 s6, s[84:85]
	s_add_i32 s65, s65, s6
	v_cmp_gt_u32_e64 s[78:79], v44, v0
	v_cmp_gt_u32_e64 s[80:81], v45, v0
	v_cmp_gt_u32_e64 s[82:83], v46, v0
	v_cmp_gt_u32_e64 s[84:85], v47, v0
	v_mov_b64_e32 v[2:3], s[70:71]
	v_mov_b64_e32 v[4:5], s[72:73]
	v_mov_b64_e32 v[6:7], s[74:75]
	v_mov_b64_e32 v[8:9], s[76:77]
	s_mov_b64 exec, s[20:21]
	ds_write_b128 v1, v[2:5] offset:64
	ds_write_b128 v1, v[6:9] offset:80
	s_mov_b64 exec, s[10:11]
	s_bcnt1_i32_b64 s6, s[70:71]
	s_add_i32 s65, s65, s6
	s_bcnt1_i32_b64 s6, s[72:73]
	s_add_i32 s65, s65, s6
	s_bcnt1_i32_b64 s6, s[74:75]
	s_add_i32 s65, s65, s6
	s_bcnt1_i32_b64 s6, s[76:77]
	s_add_i32 s65, s65, s6
	v_cmp_gt_u32_e64 s[70:71], v48, v0
	v_cmp_gt_u32_e64 s[72:73], v49, v0
	v_cmp_gt_u32_e64 s[74:75], v50, v0
	v_cmp_gt_u32_e64 s[76:77], v51, v0
	v_mov_b64_e32 v[2:3], s[78:79]
	v_mov_b64_e32 v[4:5], s[80:81]
	v_mov_b64_e32 v[6:7], s[82:83]
	v_mov_b64_e32 v[8:9], s[84:85]
	s_mov_b64 exec, s[20:21]
	ds_write_b128 v1, v[2:5] offset:96
	ds_write_b128 v1, v[6:9] offset:112
	s_mov_b64 exec, s[10:11]
	s_bcnt1_i32_b64 s6, s[78:79]
	s_add_i32 s65, s65, s6
	s_bcnt1_i32_b64 s6, s[80:81]
	s_add_i32 s65, s65, s6
	s_bcnt1_i32_b64 s6, s[82:83]
	s_add_i32 s65, s65, s6
	s_bcnt1_i32_b64 s6, s[84:85]
	s_add_i32 s65, s65, s6
	v_cmp_gt_u32_e64 s[78:79], v52, v0
	v_cmp_gt_u32_e64 s[80:81], v53, v0
	v_cmp_gt_u32_e64 s[82:83], v54, v0
	v_cmp_gt_u32_e64 s[84:85], v55, v0
	v_mov_b64_e32 v[2:3], s[70:71]
	v_mov_b64_e32 v[4:5], s[72:73]
	v_mov_b64_e32 v[6:7], s[74:75]
	v_mov_b64_e32 v[8:9], s[76:77]
	s_mov_b64 exec, s[20:21]
	ds_write_b128 v1, v[2:5] offset:128
	ds_write_b128 v1, v[6:9] offset:144
	s_mov_b64 exec, s[10:11]
	s_bcnt1_i32_b64 s6, s[70:71]
	s_add_i32 s65, s65, s6
	s_bcnt1_i32_b64 s6, s[72:73]
	s_add_i32 s65, s65, s6
	s_bcnt1_i32_b64 s6, s[74:75]
	s_add_i32 s65, s65, s6
	s_bcnt1_i32_b64 s6, s[76:77]
	s_add_i32 s65, s65, s6
	v_cmp_gt_u32_e64 s[70:71], v56, v0
	v_cmp_gt_u32_e64 s[72:73], v57, v0
	v_cmp_gt_u32_e64 s[74:75], v58, v0
	v_cmp_gt_u32_e64 s[76:77], v59, v0
	v_mov_b64_e32 v[2:3], s[78:79]
	v_mov_b64_e32 v[4:5], s[80:81]
	v_mov_b64_e32 v[6:7], s[82:83]
	v_mov_b64_e32 v[8:9], s[84:85]
	s_mov_b64 exec, s[20:21]
	ds_write_b128 v1, v[2:5] offset:160
	ds_write_b128 v1, v[6:9] offset:176
	s_mov_b64 exec, s[10:11]
	s_bcnt1_i32_b64 s6, s[78:79]
	s_add_i32 s65, s65, s6
	s_bcnt1_i32_b64 s6, s[80:81]
	s_add_i32 s65, s65, s6
	s_bcnt1_i32_b64 s6, s[82:83]
	s_add_i32 s65, s65, s6
	s_bcnt1_i32_b64 s6, s[84:85]
	s_add_i32 s65, s65, s6
	v_cmp_gt_u32_e64 s[78:79], v60, v0
	v_cmp_gt_u32_e64 s[80:81], v61, v0
	v_cmp_gt_u32_e64 s[82:83], v62, v0
	v_cmp_gt_u32_e64 s[84:85], v63, v0
	v_mov_b64_e32 v[2:3], s[70:71]
	v_mov_b64_e32 v[4:5], s[72:73]
	v_mov_b64_e32 v[6:7], s[74:75]
	v_mov_b64_e32 v[8:9], s[76:77]
	s_mov_b64 exec, s[20:21]
	ds_write_b128 v1, v[2:5] offset:192
	ds_write_b128 v1, v[6:9] offset:208
	s_mov_b64 exec, s[10:11]
	s_bcnt1_i32_b64 s6, s[70:71]
	s_add_i32 s65, s65, s6
	s_bcnt1_i32_b64 s6, s[72:73]
	s_add_i32 s65, s65, s6
	s_bcnt1_i32_b64 s6, s[74:75]
	s_add_i32 s65, s65, s6
	s_bcnt1_i32_b64 s6, s[76:77]
	s_add_i32 s65, s65, s6
	v_mov_b64_e32 v[2:3], s[78:79]
	v_mov_b64_e32 v[4:5], s[80:81]
	v_mov_b64_e32 v[6:7], s[82:83]
	v_mov_b64_e32 v[8:9], s[84:85]
	s_mov_b64 s[2:3], s[84:85]
	s_mov_b64 exec, s[20:21]
	ds_write_b128 v1, v[2:5] offset:224
	ds_write_b128 v1, v[6:9] offset:240
	s_mov_b64 exec, s[10:11]
	s_bcnt1_i32_b64 s6, s[78:79]
	s_add_i32 s65, s65, s6
	s_bcnt1_i32_b64 s6, s[80:81]
	s_add_i32 s65, s65, s6
	s_bcnt1_i32_b64 s6, s[82:83]
	s_add_i32 s65, s65, s6
	s_bcnt1_i32_b64 s6, s[84:85]
	s_add_i32 s65, s65, s6
	s_sub_i32 s14, 0x100, s65
	s_cmp_lt_i32 s14, 1
	s_cbranch_scc1 .Lpost_done
	s_mov_b32 s66, 0
	v_cmp_eq_u32_e64 s[86:87], v32, v0
	s_bcnt1_i32_b64 s6, s[86:87]
	s_cbranch_scc0 .Lpost_n0
	v_mbcnt_lo_u32_b32 v2, s86, 0
	v_mbcnt_hi_u32_b32 v2, s87, v2
	v_add_u32_e32 v2, s66, v2
	v_cmp_gt_i32_e64 s[88:89], s14, v2
	s_add_i32 s66, s66, s6
	s_and_b64 s[88:89], s[88:89], s[86:87]
	v_mov_b64_e32 v[2:3], s[88:89]
	s_mov_b64 exec, s[20:21]
	ds_or_b64 v1, v[2:3] offset:0
	s_mov_b64 exec, s[10:11]
	s_cmp_ge_i32 s66, s14
	s_cbranch_scc1 .Lpost_done
.Lpost_n0:
	v_cmp_eq_u32_e64 s[86:87], v33, v0
	s_bcnt1_i32_b64 s6, s[86:87]
	s_cbranch_scc0 .Lpost_n1
	v_mbcnt_lo_u32_b32 v2, s86, 0
	v_mbcnt_hi_u32_b32 v2, s87, v2
	v_add_u32_e32 v2, s66, v2
	v_cmp_gt_i32_e64 s[88:89], s14, v2
	s_add_i32 s66, s66, s6
	s_and_b64 s[88:89], s[88:89], s[86:87]
	v_mov_b64_e32 v[2:3], s[88:89]
	s_mov_b64 exec, s[20:21]
	ds_or_b64 v1, v[2:3] offset:8
	s_mov_b64 exec, s[10:11]
	s_cmp_ge_i32 s66, s14
	s_cbranch_scc1 .Lpost_done
.Lpost_n1:
	v_cmp_eq_u32_e64 s[86:87], v34, v0
	s_bcnt1_i32_b64 s6, s[86:87]
	s_cbranch_scc0 .Lpost_n2
	v_mbcnt_lo_u32_b32 v2, s86, 0
	v_mbcnt_hi_u32_b32 v2, s87, v2
	v_add_u32_e32 v2, s66, v2
	v_cmp_gt_i32_e64 s[88:89], s14, v2
	s_add_i32 s66, s66, s6
	s_and_b64 s[88:89], s[88:89], s[86:87]
	v_mov_b64_e32 v[2:3], s[88:89]
	s_mov_b64 exec, s[20:21]
	ds_or_b64 v1, v[2:3] offset:16
	s_mov_b64 exec, s[10:11]
	s_cmp_ge_i32 s66, s14
	s_cbranch_scc1 .Lpost_done
.Lpost_n2:
	v_cmp_eq_u32_e64 s[86:87], v35, v0
	s_bcnt1_i32_b64 s6, s[86:87]
	s_cbranch_scc0 .Lpost_n3
	v_mbcnt_lo_u32_b32 v2, s86, 0
	v_mbcnt_hi_u32_b32 v2, s87, v2
	v_add_u32_e32 v2, s66, v2
	v_cmp_gt_i32_e64 s[88:89], s14, v2
	s_add_i32 s66, s66, s6
	s_and_b64 s[88:89], s[88:89], s[86:87]
	v_mov_b64_e32 v[2:3], s[88:89]
	s_mov_b64 exec, s[20:21]
	ds_or_b64 v1, v[2:3] offset:24
	s_mov_b64 exec, s[10:11]
	s_cmp_ge_i32 s66, s14
	s_cbranch_scc1 .Lpost_done
.Lpost_n3:
	v_cmp_eq_u32_e64 s[86:87], v36, v0
	s_bcnt1_i32_b64 s6, s[86:87]
	s_cbranch_scc0 .Lpost_n4
	v_mbcnt_lo_u32_b32 v2, s86, 0
	v_mbcnt_hi_u32_b32 v2, s87, v2
	v_add_u32_e32 v2, s66, v2
	v_cmp_gt_i32_e64 s[88:89], s14, v2
	s_add_i32 s66, s66, s6
	s_and_b64 s[88:89], s[88:89], s[86:87]
	v_mov_b64_e32 v[2:3], s[88:89]
	s_mov_b64 exec, s[20:21]
	ds_or_b64 v1, v[2:3] offset:32
	s_mov_b64 exec, s[10:11]
	s_cmp_ge_i32 s66, s14
	s_cbranch_scc1 .Lpost_done
.Lpost_n4:
	v_cmp_eq_u32_e64 s[86:87], v37, v0
	s_bcnt1_i32_b64 s6, s[86:87]
	s_cbranch_scc0 .Lpost_n5
	v_mbcnt_lo_u32_b32 v2, s86, 0
	v_mbcnt_hi_u32_b32 v2, s87, v2
	v_add_u32_e32 v2, s66, v2
	v_cmp_gt_i32_e64 s[88:89], s14, v2
	s_add_i32 s66, s66, s6
	s_and_b64 s[88:89], s[88:89], s[86:87]
	v_mov_b64_e32 v[2:3], s[88:89]
	s_mov_b64 exec, s[20:21]
	ds_or_b64 v1, v[2:3] offset:40
	s_mov_b64 exec, s[10:11]
	s_cmp_ge_i32 s66, s14
	s_cbranch_scc1 .Lpost_done
.Lpost_n5:
	v_cmp_eq_u32_e64 s[86:87], v38, v0
	s_bcnt1_i32_b64 s6, s[86:87]
	s_cbranch_scc0 .Lpost_n6
	v_mbcnt_lo_u32_b32 v2, s86, 0
	v_mbcnt_hi_u32_b32 v2, s87, v2
	v_add_u32_e32 v2, s66, v2
	v_cmp_gt_i32_e64 s[88:89], s14, v2
	s_add_i32 s66, s66, s6
	s_and_b64 s[88:89], s[88:89], s[86:87]
	v_mov_b64_e32 v[2:3], s[88:89]
	s_mov_b64 exec, s[20:21]
	ds_or_b64 v1, v[2:3] offset:48
	s_mov_b64 exec, s[10:11]
	s_cmp_ge_i32 s66, s14
	s_cbranch_scc1 .Lpost_done
.Lpost_n6:
	v_cmp_eq_u32_e64 s[86:87], v39, v0
	s_bcnt1_i32_b64 s6, s[86:87]
	s_cbranch_scc0 .Lpost_n7
	v_mbcnt_lo_u32_b32 v2, s86, 0
	v_mbcnt_hi_u32_b32 v2, s87, v2
	v_add_u32_e32 v2, s66, v2
	v_cmp_gt_i32_e64 s[88:89], s14, v2
	s_add_i32 s66, s66, s6
	s_and_b64 s[88:89], s[88:89], s[86:87]
	v_mov_b64_e32 v[2:3], s[88:89]
	s_mov_b64 exec, s[20:21]
	ds_or_b64 v1, v[2:3] offset:56
	s_mov_b64 exec, s[10:11]
	s_cmp_ge_i32 s66, s14
	s_cbranch_scc1 .Lpost_done
.Lpost_n7:
	v_cmp_eq_u32_e64 s[86:87], v40, v0
	s_bcnt1_i32_b64 s6, s[86:87]
	s_cbranch_scc0 .Lpost_n8
	v_mbcnt_lo_u32_b32 v2, s86, 0
	v_mbcnt_hi_u32_b32 v2, s87, v2
	v_add_u32_e32 v2, s66, v2
	v_cmp_gt_i32_e64 s[88:89], s14, v2
	s_add_i32 s66, s66, s6
	s_and_b64 s[88:89], s[88:89], s[86:87]
	v_mov_b64_e32 v[2:3], s[88:89]
	s_mov_b64 exec, s[20:21]
	ds_or_b64 v1, v[2:3] offset:64
	s_mov_b64 exec, s[10:11]
	s_cmp_ge_i32 s66, s14
	s_cbranch_scc1 .Lpost_done
.Lpost_n8:
	v_cmp_eq_u32_e64 s[86:87], v41, v0
	s_bcnt1_i32_b64 s6, s[86:87]
	s_cbranch_scc0 .Lpost_n9
	v_mbcnt_lo_u32_b32 v2, s86, 0
	v_mbcnt_hi_u32_b32 v2, s87, v2
	v_add_u32_e32 v2, s66, v2
	v_cmp_gt_i32_e64 s[88:89], s14, v2
	s_add_i32 s66, s66, s6
	s_and_b64 s[88:89], s[88:89], s[86:87]
	v_mov_b64_e32 v[2:3], s[88:89]
	s_mov_b64 exec, s[20:21]
	ds_or_b64 v1, v[2:3] offset:72
	s_mov_b64 exec, s[10:11]
	s_cmp_ge_i32 s66, s14
	s_cbranch_scc1 .Lpost_done
.Lpost_n9:
	v_cmp_eq_u32_e64 s[86:87], v42, v0
	s_bcnt1_i32_b64 s6, s[86:87]
	s_cbranch_scc0 .Lpost_n10
	v_mbcnt_lo_u32_b32 v2, s86, 0
	v_mbcnt_hi_u32_b32 v2, s87, v2
	v_add_u32_e32 v2, s66, v2
	v_cmp_gt_i32_e64 s[88:89], s14, v2
	s_add_i32 s66, s66, s6
	s_and_b64 s[88:89], s[88:89], s[86:87]
	v_mov_b64_e32 v[2:3], s[88:89]
	s_mov_b64 exec, s[20:21]
	ds_or_b64 v1, v[2:3] offset:80
	s_mov_b64 exec, s[10:11]
	s_cmp_ge_i32 s66, s14
	s_cbranch_scc1 .Lpost_done
.Lpost_n10:
	v_cmp_eq_u32_e64 s[86:87], v43, v0
	s_bcnt1_i32_b64 s6, s[86:87]
	s_cbranch_scc0 .Lpost_n11
	v_mbcnt_lo_u32_b32 v2, s86, 0
	v_mbcnt_hi_u32_b32 v2, s87, v2
	v_add_u32_e32 v2, s66, v2
	v_cmp_gt_i32_e64 s[88:89], s14, v2
	s_add_i32 s66, s66, s6
	s_and_b64 s[88:89], s[88:89], s[86:87]
	v_mov_b64_e32 v[2:3], s[88:89]
	s_mov_b64 exec, s[20:21]
	ds_or_b64 v1, v[2:3] offset:88
	s_mov_b64 exec, s[10:11]
	s_cmp_ge_i32 s66, s14
	s_cbranch_scc1 .Lpost_done
.Lpost_n11:
	v_cmp_eq_u32_e64 s[86:87], v44, v0
	s_bcnt1_i32_b64 s6, s[86:87]
	s_cbranch_scc0 .Lpost_n12
	v_mbcnt_lo_u32_b32 v2, s86, 0
	v_mbcnt_hi_u32_b32 v2, s87, v2
	v_add_u32_e32 v2, s66, v2
	v_cmp_gt_i32_e64 s[88:89], s14, v2
	s_add_i32 s66, s66, s6
	s_and_b64 s[88:89], s[88:89], s[86:87]
	v_mov_b64_e32 v[2:3], s[88:89]
	s_mov_b64 exec, s[20:21]
	ds_or_b64 v1, v[2:3] offset:96
	s_mov_b64 exec, s[10:11]
	s_cmp_ge_i32 s66, s14
	s_cbranch_scc1 .Lpost_done
.Lpost_n12:
	v_cmp_eq_u32_e64 s[86:87], v45, v0
	s_bcnt1_i32_b64 s6, s[86:87]
	s_cbranch_scc0 .Lpost_n13
	v_mbcnt_lo_u32_b32 v2, s86, 0
	v_mbcnt_hi_u32_b32 v2, s87, v2
	v_add_u32_e32 v2, s66, v2
	v_cmp_gt_i32_e64 s[88:89], s14, v2
	s_add_i32 s66, s66, s6
	s_and_b64 s[88:89], s[88:89], s[86:87]
	v_mov_b64_e32 v[2:3], s[88:89]
	s_mov_b64 exec, s[20:21]
	ds_or_b64 v1, v[2:3] offset:104
	s_mov_b64 exec, s[10:11]
	s_cmp_ge_i32 s66, s14
	s_cbranch_scc1 .Lpost_done
.Lpost_n13:
	v_cmp_eq_u32_e64 s[86:87], v46, v0
	s_bcnt1_i32_b64 s6, s[86:87]
	s_cbranch_scc0 .Lpost_n14
	v_mbcnt_lo_u32_b32 v2, s86, 0
	v_mbcnt_hi_u32_b32 v2, s87, v2
	v_add_u32_e32 v2, s66, v2
	v_cmp_gt_i32_e64 s[88:89], s14, v2
	s_add_i32 s66, s66, s6
	s_and_b64 s[88:89], s[88:89], s[86:87]
	v_mov_b64_e32 v[2:3], s[88:89]
	s_mov_b64 exec, s[20:21]
	ds_or_b64 v1, v[2:3] offset:112
	s_mov_b64 exec, s[10:11]
	s_cmp_ge_i32 s66, s14
	s_cbranch_scc1 .Lpost_done
.Lpost_n14:
	v_cmp_eq_u32_e64 s[86:87], v47, v0
	s_bcnt1_i32_b64 s6, s[86:87]
	s_cbranch_scc0 .Lpost_n15
	v_mbcnt_lo_u32_b32 v2, s86, 0
	v_mbcnt_hi_u32_b32 v2, s87, v2
	v_add_u32_e32 v2, s66, v2
	v_cmp_gt_i32_e64 s[88:89], s14, v2
	s_add_i32 s66, s66, s6
	s_and_b64 s[88:89], s[88:89], s[86:87]
	v_mov_b64_e32 v[2:3], s[88:89]
	s_mov_b64 exec, s[20:21]
	ds_or_b64 v1, v[2:3] offset:120
	s_mov_b64 exec, s[10:11]
	s_cmp_ge_i32 s66, s14
	s_cbranch_scc1 .Lpost_done
.Lpost_n15:
	v_cmp_eq_u32_e64 s[86:87], v48, v0
	s_bcnt1_i32_b64 s6, s[86:87]
	s_cbranch_scc0 .Lpost_n16
	v_mbcnt_lo_u32_b32 v2, s86, 0
	v_mbcnt_hi_u32_b32 v2, s87, v2
	v_add_u32_e32 v2, s66, v2
	v_cmp_gt_i32_e64 s[88:89], s14, v2
	s_add_i32 s66, s66, s6
	s_and_b64 s[88:89], s[88:89], s[86:87]
	v_mov_b64_e32 v[2:3], s[88:89]
	s_mov_b64 exec, s[20:21]
	ds_or_b64 v1, v[2:3] offset:128
	s_mov_b64 exec, s[10:11]
	s_cmp_ge_i32 s66, s14
	s_cbranch_scc1 .Lpost_done
.Lpost_n16:
	v_cmp_eq_u32_e64 s[86:87], v49, v0
	s_bcnt1_i32_b64 s6, s[86:87]
	s_cbranch_scc0 .Lpost_n17
	v_mbcnt_lo_u32_b32 v2, s86, 0
	v_mbcnt_hi_u32_b32 v2, s87, v2
	v_add_u32_e32 v2, s66, v2
	v_cmp_gt_i32_e64 s[88:89], s14, v2
	s_add_i32 s66, s66, s6
	s_and_b64 s[88:89], s[88:89], s[86:87]
	v_mov_b64_e32 v[2:3], s[88:89]
	s_mov_b64 exec, s[20:21]
	ds_or_b64 v1, v[2:3] offset:136
	s_mov_b64 exec, s[10:11]
	s_cmp_ge_i32 s66, s14
	s_cbranch_scc1 .Lpost_done
.Lpost_n17:
	v_cmp_eq_u32_e64 s[86:87], v50, v0
	s_bcnt1_i32_b64 s6, s[86:87]
	s_cbranch_scc0 .Lpost_n18
	v_mbcnt_lo_u32_b32 v2, s86, 0
	v_mbcnt_hi_u32_b32 v2, s87, v2
	v_add_u32_e32 v2, s66, v2
	v_cmp_gt_i32_e64 s[88:89], s14, v2
	s_add_i32 s66, s66, s6
	s_and_b64 s[88:89], s[88:89], s[86:87]
	v_mov_b64_e32 v[2:3], s[88:89]
	s_mov_b64 exec, s[20:21]
	ds_or_b64 v1, v[2:3] offset:144
	s_mov_b64 exec, s[10:11]
	s_cmp_ge_i32 s66, s14
	s_cbranch_scc1 .Lpost_done
.Lpost_n18:
	v_cmp_eq_u32_e64 s[86:87], v51, v0
	s_bcnt1_i32_b64 s6, s[86:87]
	s_cbranch_scc0 .Lpost_n19
	v_mbcnt_lo_u32_b32 v2, s86, 0
	v_mbcnt_hi_u32_b32 v2, s87, v2
	v_add_u32_e32 v2, s66, v2
	v_cmp_gt_i32_e64 s[88:89], s14, v2
	s_add_i32 s66, s66, s6
	s_and_b64 s[88:89], s[88:89], s[86:87]
	v_mov_b64_e32 v[2:3], s[88:89]
	s_mov_b64 exec, s[20:21]
	ds_or_b64 v1, v[2:3] offset:152
	s_mov_b64 exec, s[10:11]
	s_cmp_ge_i32 s66, s14
	s_cbranch_scc1 .Lpost_done
.Lpost_n19:
	v_cmp_eq_u32_e64 s[86:87], v52, v0
	s_bcnt1_i32_b64 s6, s[86:87]
	s_cbranch_scc0 .Lpost_n20
	v_mbcnt_lo_u32_b32 v2, s86, 0
	v_mbcnt_hi_u32_b32 v2, s87, v2
	v_add_u32_e32 v2, s66, v2
	v_cmp_gt_i32_e64 s[88:89], s14, v2
	s_add_i32 s66, s66, s6
	s_and_b64 s[88:89], s[88:89], s[86:87]
	v_mov_b64_e32 v[2:3], s[88:89]
	s_mov_b64 exec, s[20:21]
	ds_or_b64 v1, v[2:3] offset:160
	s_mov_b64 exec, s[10:11]
	s_cmp_ge_i32 s66, s14
	s_cbranch_scc1 .Lpost_done
.Lpost_n20:
	v_cmp_eq_u32_e64 s[86:87], v53, v0
	s_bcnt1_i32_b64 s6, s[86:87]
	s_cbranch_scc0 .Lpost_n21
	v_mbcnt_lo_u32_b32 v2, s86, 0
	v_mbcnt_hi_u32_b32 v2, s87, v2
	v_add_u32_e32 v2, s66, v2
	v_cmp_gt_i32_e64 s[88:89], s14, v2
	s_add_i32 s66, s66, s6
	s_and_b64 s[88:89], s[88:89], s[86:87]
	v_mov_b64_e32 v[2:3], s[88:89]
	s_mov_b64 exec, s[20:21]
	ds_or_b64 v1, v[2:3] offset:168
	s_mov_b64 exec, s[10:11]
	s_cmp_ge_i32 s66, s14
	s_cbranch_scc1 .Lpost_done
.Lpost_n21:
	v_cmp_eq_u32_e64 s[86:87], v54, v0
	s_bcnt1_i32_b64 s6, s[86:87]
	s_cbranch_scc0 .Lpost_n22
	v_mbcnt_lo_u32_b32 v2, s86, 0
	v_mbcnt_hi_u32_b32 v2, s87, v2
	v_add_u32_e32 v2, s66, v2
	v_cmp_gt_i32_e64 s[88:89], s14, v2
	s_add_i32 s66, s66, s6
	s_and_b64 s[88:89], s[88:89], s[86:87]
	v_mov_b64_e32 v[2:3], s[88:89]
	s_mov_b64 exec, s[20:21]
	ds_or_b64 v1, v[2:3] offset:176
	s_mov_b64 exec, s[10:11]
	s_cmp_ge_i32 s66, s14
	s_cbranch_scc1 .Lpost_done
.Lpost_n22:
	v_cmp_eq_u32_e64 s[86:87], v55, v0
	s_bcnt1_i32_b64 s6, s[86:87]
	s_cbranch_scc0 .Lpost_n23
	v_mbcnt_lo_u32_b32 v2, s86, 0
	v_mbcnt_hi_u32_b32 v2, s87, v2
	v_add_u32_e32 v2, s66, v2
	v_cmp_gt_i32_e64 s[88:89], s14, v2
	s_add_i32 s66, s66, s6
	s_and_b64 s[88:89], s[88:89], s[86:87]
	v_mov_b64_e32 v[2:3], s[88:89]
	s_mov_b64 exec, s[20:21]
	ds_or_b64 v1, v[2:3] offset:184
	s_mov_b64 exec, s[10:11]
	s_cmp_ge_i32 s66, s14
	s_cbranch_scc1 .Lpost_done
.Lpost_n23:
	v_cmp_eq_u32_e64 s[86:87], v56, v0
	s_bcnt1_i32_b64 s6, s[86:87]
	s_cbranch_scc0 .Lpost_n24
	v_mbcnt_lo_u32_b32 v2, s86, 0
	v_mbcnt_hi_u32_b32 v2, s87, v2
	v_add_u32_e32 v2, s66, v2
	v_cmp_gt_i32_e64 s[88:89], s14, v2
	s_add_i32 s66, s66, s6
	s_and_b64 s[88:89], s[88:89], s[86:87]
	v_mov_b64_e32 v[2:3], s[88:89]
	s_mov_b64 exec, s[20:21]
	ds_or_b64 v1, v[2:3] offset:192
	s_mov_b64 exec, s[10:11]
	s_cmp_ge_i32 s66, s14
	s_cbranch_scc1 .Lpost_done
.Lpost_n24:
	v_cmp_eq_u32_e64 s[86:87], v57, v0
	s_bcnt1_i32_b64 s6, s[86:87]
	s_cbranch_scc0 .Lpost_n25
	v_mbcnt_lo_u32_b32 v2, s86, 0
	v_mbcnt_hi_u32_b32 v2, s87, v2
	v_add_u32_e32 v2, s66, v2
	v_cmp_gt_i32_e64 s[88:89], s14, v2
	s_add_i32 s66, s66, s6
	s_and_b64 s[88:89], s[88:89], s[86:87]
	v_mov_b64_e32 v[2:3], s[88:89]
	s_mov_b64 exec, s[20:21]
	ds_or_b64 v1, v[2:3] offset:200
	s_mov_b64 exec, s[10:11]
	s_cmp_ge_i32 s66, s14
	s_cbranch_scc1 .Lpost_done
.Lpost_n25:
	v_cmp_eq_u32_e64 s[86:87], v58, v0
	s_bcnt1_i32_b64 s6, s[86:87]
	s_cbranch_scc0 .Lpost_n26
	v_mbcnt_lo_u32_b32 v2, s86, 0
	v_mbcnt_hi_u32_b32 v2, s87, v2
	v_add_u32_e32 v2, s66, v2
	v_cmp_gt_i32_e64 s[88:89], s14, v2
	s_add_i32 s66, s66, s6
	s_and_b64 s[88:89], s[88:89], s[86:87]
	v_mov_b64_e32 v[2:3], s[88:89]
	s_mov_b64 exec, s[20:21]
	ds_or_b64 v1, v[2:3] offset:208
	s_mov_b64 exec, s[10:11]
	s_cmp_ge_i32 s66, s14
	s_cbranch_scc1 .Lpost_done
.Lpost_n26:
	v_cmp_eq_u32_e64 s[86:87], v59, v0
	s_bcnt1_i32_b64 s6, s[86:87]
	s_cbranch_scc0 .Lpost_n27
	v_mbcnt_lo_u32_b32 v2, s86, 0
	v_mbcnt_hi_u32_b32 v2, s87, v2
	v_add_u32_e32 v2, s66, v2
	v_cmp_gt_i32_e64 s[88:89], s14, v2
	s_add_i32 s66, s66, s6
	s_and_b64 s[88:89], s[88:89], s[86:87]
	v_mov_b64_e32 v[2:3], s[88:89]
	s_mov_b64 exec, s[20:21]
	ds_or_b64 v1, v[2:3] offset:216
	s_mov_b64 exec, s[10:11]
	s_cmp_ge_i32 s66, s14
	s_cbranch_scc1 .Lpost_done
.Lpost_n27:
	v_cmp_eq_u32_e64 s[86:87], v60, v0
	s_bcnt1_i32_b64 s6, s[86:87]
	s_cbranch_scc0 .Lpost_n28
	v_mbcnt_lo_u32_b32 v2, s86, 0
	v_mbcnt_hi_u32_b32 v2, s87, v2
	v_add_u32_e32 v2, s66, v2
	v_cmp_gt_i32_e64 s[88:89], s14, v2
	s_add_i32 s66, s66, s6
	s_and_b64 s[88:89], s[88:89], s[86:87]
	v_mov_b64_e32 v[2:3], s[88:89]
	s_mov_b64 exec, s[20:21]
	ds_or_b64 v1, v[2:3] offset:224
	s_mov_b64 exec, s[10:11]
	s_cmp_ge_i32 s66, s14
	s_cbranch_scc1 .Lpost_done
.Lpost_n28:
	v_cmp_eq_u32_e64 s[86:87], v61, v0
	s_bcnt1_i32_b64 s6, s[86:87]
	s_cbranch_scc0 .Lpost_n29
	v_mbcnt_lo_u32_b32 v2, s86, 0
	v_mbcnt_hi_u32_b32 v2, s87, v2
	v_add_u32_e32 v2, s66, v2
	v_cmp_gt_i32_e64 s[88:89], s14, v2
	s_add_i32 s66, s66, s6
	s_and_b64 s[88:89], s[88:89], s[86:87]
	v_mov_b64_e32 v[2:3], s[88:89]
	s_mov_b64 exec, s[20:21]
	ds_or_b64 v1, v[2:3] offset:232
	s_mov_b64 exec, s[10:11]
	s_cmp_ge_i32 s66, s14
	s_cbranch_scc1 .Lpost_done
.Lpost_n29:
	v_cmp_eq_u32_e64 s[86:87], v62, v0
	s_bcnt1_i32_b64 s6, s[86:87]
	s_cbranch_scc0 .Lpost_n30
	v_mbcnt_lo_u32_b32 v2, s86, 0
	v_mbcnt_hi_u32_b32 v2, s87, v2
	v_add_u32_e32 v2, s66, v2
	v_cmp_gt_i32_e64 s[88:89], s14, v2
	s_add_i32 s66, s66, s6
	s_and_b64 s[88:89], s[88:89], s[86:87]
	v_mov_b64_e32 v[2:3], s[88:89]
	s_mov_b64 exec, s[20:21]
	ds_or_b64 v1, v[2:3] offset:240
	s_mov_b64 exec, s[10:11]
	s_cmp_ge_i32 s66, s14
	s_cbranch_scc1 .Lpost_done
.Lpost_n30:
	v_cmp_eq_u32_e64 s[86:87], v63, v0
	s_bcnt1_i32_b64 s6, s[86:87]
	s_cbranch_scc0 .Lpost_n31
	v_mbcnt_lo_u32_b32 v2, s86, 0
	v_mbcnt_hi_u32_b32 v2, s87, v2
	v_add_u32_e32 v2, s66, v2
	v_cmp_gt_i32_e64 s[88:89], s14, v2
	s_add_i32 s66, s66, s6
	s_and_b64 s[88:89], s[88:89], s[86:87]
	s_or_b64 s[2:3], s[2:3], s[88:89]
	v_mov_b64_e32 v[2:3], s[88:89]
	s_mov_b64 exec, s[20:21]
	ds_or_b64 v1, v[2:3] offset:248
	s_mov_b64 exec, s[10:11]
	s_cmp_ge_i32 s66, s14
	s_cbranch_scc1 .Lpost_done
.Lpost_n31:
.Lpost_done:
	s_mov_b64 s[0:1], s[20:21]
	s_branch .LBB0_648
